# v20 plus: m0 save/restore pairs removed around the six LDS-DMAs of the attention steady loop (placement of all later code kept with pad)
# baseline (speedup 1.0000x reference)
; #define WAIT_BAR(N) asm volatile("s_waitcnt vmcnt(" #N ") lgkmcnt(0)\n\ts_barrier":::"memory")
;   #define RESC() do{ if(resc){ asm volatile("s_waitcnt lgkmcnt(0)":::"memory"); \
;       _Pragma("unroll") for(int d_=0;d_<2;++d_) _Pragma("unroll") for(int r=0;r<16;++r){const float f_=wsf[crow(r,hi)];o[d_][r]*=f_;o2[d_][r]*=f_;} } }while(0)
;   #define ROT() do{sl_prev=sl_cur;sl_cur=sl_next;sl_next=(sl_next==(NSLOT-1)*SLOTB)?0:sl_next+SLOTB;}while(0)
; template<int THRL> __device__ __forceinline__ void attn_unit(int b,int h,int qb,unsigned char*wsb,char*shm,float kmax,const int CMB,float lam){
;     ...
;   int t=1;
;     ...
;   for(;t+5<NT;t+=2){
;     STEP(pB0,pB1,pA0,pA1,t,true,true,true);     WAIT_BAR(3); RESC(); ROT();
.LBB0_311:
	s_mov_b32 s37, s36
	s_mov_b32 s4, s33
	s_mov_b32 s1, s42
	v_add_u32_e32 v209, s5, v252
	ds_read_b64_tr_b16 v[216:217], v209 offset:24576
	ds_read_b64_tr_b16 v[218:219], v209 offset:25088
	v_add_f32_e32 v65, v96, v97
	v_add_f32_e32 v65, v98, v65
	v_add_f32_e32 v65, v99, v65
	v_add_f32_e32 v65, v100, v65
	v_add_f32_e32 v65, v101, v65
	v_cvt_pk_bf16_f32 v172, v96, v97
	v_cvt_pk_bf16_f32 v173, v98, v99
	s_waitcnt lgkmcnt(9)
	v_mfma_f32_32x32x16_bf16 v[128:143], v[204:207], v[156:159], v[230:245]
	ds_read_b64_tr_b16 v[204:205], v209 offset:28672
	ds_read_b64_tr_b16 v[206:207], v209 offset:29184
	v_add_f32_e32 v65, v102, v65
	v_add_f32_e32 v65, v103, v65
	v_add_f32_e32 v65, v104, v65
	v_add_f32_e32 v65, v105, v65
	v_cvt_pk_bf16_f32 v174, v100, v101
	v_cvt_pk_bf16_f32 v175, v102, v103
	s_waitcnt lgkmcnt(10)
	v_mfma_f32_32x32x16_bf16 v[112:127], v[200:203], v[156:159], v[230:245]
	ds_read_b64_tr_b16 v[74:75], v209 offset:25600
	ds_read_b64_tr_b16 v[76:77], v209 offset:26112
	v_add_f32_e32 v65, v106, v65
	v_add_f32_e32 v65, v107, v65
	v_add_f32_e32 v65, v108, v65
	v_add_f32_e32 v65, v109, v65
	v_cvt_pk_bf16_f32 v168, v104, v105
	v_cvt_pk_bf16_f32 v169, v106, v107
	s_waitcnt lgkmcnt(11)
	v_mfma_f32_32x32x16_bf16 v[128:143], v[196:199], v[152:155], v[128:143]
	ds_read_b64_tr_b16 v[70:71], v209 offset:29696
	ds_read_b64_tr_b16 v[72:73], v209 offset:30208
	v_add_f32_e32 v65, v110, v65
	v_add_f32_e32 v65, v111, v65
	v_add_f32_e32 v65, v80, v65
	v_add_f32_e32 v65, v81, v65
	v_cvt_pk_bf16_f32 v170, v108, v109
	v_cvt_pk_bf16_f32 v171, v110, v111
	s_waitcnt lgkmcnt(12)
	v_mfma_f32_32x32x16_bf16 v[112:127], v[192:195], v[152:155], v[112:127]
	ds_read_b64_tr_b16 v[66:67], v209 offset:26624
	ds_read_b64_tr_b16 v[68:69], v209 offset:27136
	v_add_f32_e32 v65, v82, v65
	v_add_f32_e32 v65, v83, v65
	v_add_f32_e32 v65, v84, v65
	v_add_f32_e32 v65, v85, v65
	v_cvt_pk_bf16_f32 v164, v80, v81
	v_cvt_pk_bf16_f32 v165, v82, v83
	s_waitcnt lgkmcnt(13)
	v_mfma_f32_32x32x16_bf16 v[128:143], v[188:191], v[148:151], v[128:143]
	ds_read_b64_tr_b16 v[100:101], v209 offset:30720
	ds_read_b64_tr_b16 v[102:103], v209 offset:31232
	v_add_f32_e32 v65, v86, v65
	v_add_f32_e32 v65, v87, v65
	v_add_f32_e32 v65, v88, v65
	v_add_f32_e32 v65, v89, v65
	v_cvt_pk_bf16_f32 v166, v84, v85
	v_cvt_pk_bf16_f32 v167, v86, v87
	s_waitcnt lgkmcnt(14)
	v_mfma_f32_32x32x16_bf16 v[112:127], v[184:187], v[148:151], v[112:127]
	ds_read_b64_tr_b16 v[96:97], v209 offset:27648
	ds_read_b64_tr_b16 v[98:99], v209 offset:28160
	v_add_f32_e32 v65, v90, v65
	v_add_f32_e32 v65, v91, v65
	v_add_f32_e32 v65, v92, v65
	v_add_f32_e32 v65, v93, v65
	v_cvt_pk_bf16_f32 v160, v88, v89
	v_cvt_pk_bf16_f32 v161, v90, v91
	s_waitcnt lgkmcnt(14)
	v_mfma_f32_32x32x16_bf16 v[128:143], v[180:183], v[144:147], v[128:143]
	ds_read_b64_tr_b16 v[86:87], v209 offset:31744
	ds_read_b64_tr_b16 v[88:89], v209 offset:32256
	v_add_f32_e32 v65, v94, v65
	v_add_f32_e32 v65, v95, v65
	v_add_f32_e32 v65, 0, v65
	v_cvt_pk_bf16_f32 v162, v92, v93
	v_cvt_pk_bf16_f32 v163, v94, v95
	v_mfma_f32_32x32x16_bf16 v[112:127], v[176:179], v[144:147], v[112:127]
	v_lshl_add_u64 v[190:191], v[212:213], 0, s[48:49]
	v_lshl_add_u64 v[78:79], v[190:191], 0, s[10:11]
	s_add_i32 s5, s42, s3
	s_mov_b32 m0, s5
	s_nop 0
	global_load_lds_dwordx4 v[78:79], off
	v_lshl_add_u64 v[188:189], v[210:211], 0, s[48:49]
	v_lshl_add_u64 v[78:79], v[188:189], 0, s[12:13]
	s_add_i32 s5, s36, s97
	s_mov_b32 m0, s5
	s_nop 0
	global_load_lds_dwordx4 v[78:79], off
	v_lshl_add_u64 v[78:79], v[188:189], 0, s[14:15]
	s_add_i32 s5, s36, s96
	s_mov_b32 m0, s5
	s_nop 0
	global_load_lds_dwordx4 v[78:79], off
	s_waitcnt lgkmcnt(14)
	v_mfma_f32_32x32x16_bf16 v[32:47], v[172:175], v[216:219], v[32:47]
	v_exp_f32_e32 v128, v128
	v_exp_f32_e32 v129, v129
	ds_read_b64_tr_b16 v[90:91], v209 offset:49152
	ds_read_b64_tr_b16 v[92:93], v209 offset:49664
	s_waitcnt lgkmcnt(14)
	v_mfma_f32_32x32x16_bf16 v[48:63], v[172:175], v[204:207], v[48:63]
	v_exp_f32_e32 v130, v130
	v_exp_f32_e32 v131, v131
	ds_read_b64_tr_b16 v[104:105], v209 offset:53248
	ds_read_b64_tr_b16 v[106:107], v209 offset:53760
	v_add_u32_e32 v94, s37, v250
	ds_read_b128 v[82:85], v94
	ds_read_b128 v[78:81], v94 offset:512
	s_waitcnt lgkmcnt(14)
	v_mfma_f32_32x32x16_bf16 v[32:47], v[168:171], v[74:77], v[32:47]
	v_exp_f32_e32 v132, v132
	v_exp_f32_e32 v133, v133
	ds_read_b64_tr_b16 v[108:109], v209 offset:50176
	ds_read_b64_tr_b16 v[110:111], v209 offset:50688
	ds_read_b128 v[184:187], v94 offset:2048
	ds_read_b128 v[176:179], v94 offset:2560
	v_mfma_f32_32x32x16_bf16 v[48:63], v[168:171], v[70:73], v[48:63]
	v_exp_f32_e32 v134, v134
	v_exp_f32_e32 v135, v135
	ds_read_b64_tr_b16 v[192:193], v209 offset:54272
	ds_read_b64_tr_b16 v[194:195], v209 offset:54784
	ds_read_b128 v[180:183], v94 offset:4096
	ds_read_b128 v[70:73], v94 offset:4608
	s_waitcnt lgkmcnt(14)
	v_mfma_f32_32x32x16_bf16 v[32:47], v[164:167], v[66:69], v[32:47]
	v_exp_f32_e32 v136, v136
	v_exp_f32_e32 v137, v137
	ds_read_b64_tr_b16 v[196:197], v209 offset:51200
	ds_read_b64_tr_b16 v[198:199], v209 offset:51712
	ds_read_b128 v[74:77], v94 offset:6144
	ds_read_b128 v[66:69], v94 offset:6656
	v_mfma_f32_32x32x16_bf16 v[48:63], v[164:167], v[100:103], v[48:63]
	v_exp_f32_e32 v138, v138
	v_exp_f32_e32 v139, v139
	ds_read_b64_tr_b16 v[100:101], v209 offset:55296
	ds_read_b64_tr_b16 v[102:103], v209 offset:55808
	v_mfma_f32_32x32x16_bf16 v[32:47], v[160:163], v[96:99], v[32:47]
	v_exp_f32_e32 v140, v140
	v_exp_f32_e32 v141, v141
	ds_read_b64_tr_b16 v[94:95], v209 offset:52224
	ds_read_b64_tr_b16 v[96:97], v209 offset:52736
	v_mfma_f32_32x32x16_bf16 v[48:63], v[160:163], v[86:89], v[48:63]
	v_exp_f32_e32 v142, v142
	v_exp_f32_e32 v143, v143
	ds_read_b64_tr_b16 v[86:87], v209 offset:56320
	ds_read_b64_tr_b16 v[88:89], v209 offset:56832
	s_waitcnt lgkmcnt(14)
	v_mfma_f32_32x32x16_bf16 v[0:15], v[172:175], v[90:93], v[0:15]
	v_exp_f32_e32 v112, v112
	v_exp_f32_e32 v113, v113
	v_mfma_f32_32x32x16_bf16 v[16:31], v[172:175], v[104:107], v[16:31]
	v_exp_f32_e32 v114, v114
	v_exp_f32_e32 v115, v115
	v_mfma_f32_32x32x16_bf16 v[0:15], v[168:171], v[108:111], v[0:15]
	v_exp_f32_e32 v116, v116
	v_exp_f32_e32 v117, v117
	s_waitcnt lgkmcnt(12)
	v_mfma_f32_32x32x16_bf16 v[16:31], v[168:171], v[192:195], v[16:31]
	v_exp_f32_e32 v118, v118
	v_exp_f32_e32 v119, v119
	s_waitcnt lgkmcnt(8)
	v_mfma_f32_32x32x16_bf16 v[0:15], v[164:167], v[196:199], v[0:15]
	v_exp_f32_e32 v120, v120
	v_exp_f32_e32 v121, v121
	s_waitcnt lgkmcnt(4)
	v_mfma_f32_32x32x16_bf16 v[16:31], v[164:167], v[100:103], v[16:31]
	v_exp_f32_e32 v122, v122
	v_exp_f32_e32 v123, v123
	s_waitcnt lgkmcnt(2)
	v_mfma_f32_32x32x16_bf16 v[0:15], v[160:163], v[94:97], v[0:15]
	v_exp_f32_e32 v124, v124
	v_exp_f32_e32 v125, v125
	s_waitcnt lgkmcnt(0)
	v_mfma_f32_32x32x16_bf16 v[16:31], v[160:163], v[86:89], v[16:31]
	v_exp_f32_e32 v126, v126
	v_exp_f32_e32 v127, v127
	s_waitcnt vmcnt(3) lgkmcnt(0)
	s_barrier
	s_add_i32 s5, s36, 0x2000
	s_cmpk_lg_i32 s36, 0x4000
	s_cselect_b32 s42, s5, 0
	v_add_u32_e32 v209, s1, v252
	ds_read_b64_tr_b16 v[192:193], v209 offset:24576
	ds_read_b64_tr_b16 v[194:195], v209 offset:25088
	v_mfma_f32_32x32x16_bf16 v[96:111], v[82:85], v[156:159], v[230:245]
	v_add_f32_e32 v86, v128, v129
	v_add_f32_e32 v86, v130, v86
	v_add_f32_e32 v86, v131, v86
	v_add_f32_e32 v86, v132, v86
	v_add_f32_e32 v86, v133, v86
	v_cvt_pk_bf16_f32 v172, v128, v129
	v_cvt_pk_bf16_f32 v173, v130, v131
	ds_read_b64_tr_b16 v[196:197], v209 offset:28672
	ds_read_b64_tr_b16 v[198:199], v209 offset:29184
	v_add_f32_e32 v82, v134, v86
	v_add_f32_e32 v82, v135, v82
	v_add_f32_e32 v82, v136, v82
	v_add_f32_e32 v128, v137, v82
	v_mfma_f32_32x32x16_bf16 v[80:95], v[78:81], v[156:159], v[230:245]
	v_cvt_pk_bf16_f32 v174, v132, v133
	v_cvt_pk_bf16_f32 v175, v134, v135
	ds_read_b64_tr_b16 v[216:217], v209 offset:25600
	ds_read_b64_tr_b16 v[218:219], v209 offset:26112
	v_mfma_f32_32x32x16_bf16 v[96:111], v[184:187], v[152:155], v[96:111]
	v_add_f32_e32 v78, v138, v128
	v_add_f32_e32 v78, v139, v78
	v_add_f32_e32 v78, v140, v78
	v_add_f32_e32 v78, v141, v78
	v_cvt_pk_bf16_f32 v168, v136, v137
	v_cvt_pk_bf16_f32 v169, v138, v139
	ds_read_b64_tr_b16 v[136:137], v209 offset:29696
	ds_read_b64_tr_b16 v[138:139], v209 offset:30208
	v_mfma_f32_32x32x16_bf16 v[80:95], v[176:179], v[152:155], v[80:95]
	v_add_f32_e32 v78, v142, v78
	v_add_f32_e32 v78, v143, v78
	v_add_f32_e32 v78, v112, v78
	v_add_f32_e32 v78, v113, v78
	v_cvt_pk_bf16_f32 v170, v140, v141
	v_cvt_pk_bf16_f32 v171, v142, v143
	ds_read_b64_tr_b16 v[132:133], v209 offset:26624
	ds_read_b64_tr_b16 v[134:135], v209 offset:27136
	v_mfma_f32_32x32x16_bf16 v[96:111], v[180:183], v[148:151], v[96:111]
	v_add_f32_e32 v78, v114, v78
	v_add_f32_e32 v78, v115, v78
	v_add_f32_e32 v78, v116, v78
	v_add_f32_e32 v78, v117, v78
	v_cvt_pk_bf16_f32 v164, v112, v113
	v_cvt_pk_bf16_f32 v165, v114, v115
	ds_read_b64_tr_b16 v[128:129], v209 offset:30720
	ds_read_b64_tr_b16 v[130:131], v209 offset:31232
	v_mfma_f32_32x32x16_bf16 v[80:95], v[70:73], v[148:151], v[80:95]
	v_add_f32_e32 v78, v118, v78
	v_add_f32_e32 v78, v119, v78
	v_add_f32_e32 v78, v120, v78
	v_add_f32_e32 v78, v121, v78
	v_cvt_pk_bf16_f32 v166, v116, v117
	v_cvt_pk_bf16_f32 v167, v118, v119
	ds_read_b64_tr_b16 v[112:113], v209 offset:27648
	ds_read_b64_tr_b16 v[114:115], v209 offset:28160
	v_mfma_f32_32x32x16_bf16 v[96:111], v[74:77], v[144:147], v[96:111]
	v_add_f32_e32 v70, v122, v78
	v_add_f32_e32 v70, v123, v70
	v_add_f32_e32 v70, v124, v70
	v_add_f32_e32 v78, v125, v70
	v_cvt_pk_bf16_f32 v160, v120, v121
	v_cvt_pk_bf16_f32 v161, v122, v123
	ds_read_b64_tr_b16 v[70:71], v209 offset:31744
	ds_read_b64_tr_b16 v[72:73], v209 offset:32256
	v_mfma_f32_32x32x16_bf16 v[80:95], v[66:69], v[144:147], v[80:95]
	v_add_f32_e32 v74, v126, v78
	v_add_f32_e32 v74, v127, v74
	v_add_f32_e32 v74, 0, v74
	v_cvt_pk_bf16_f32 v162, v124, v125
	v_cvt_pk_bf16_f32 v163, v126, v127
	v_lshl_add_u64 v[66:67], v[190:191], 0, s[16:17]
	s_add_i32 s1, s36, s3
	s_mov_b32 m0, s1
	s_nop 0
	global_load_lds_dwordx4 v[66:67], off
	v_lshl_add_u64 v[66:67], v[188:189], 0, s[18:19]
	s_add_i32 s1, s42, s97
	s_mov_b32 m0, s1
	s_nop 0
	global_load_lds_dwordx4 v[66:67], off
	v_lshl_add_u64 v[66:67], v[188:189], 0, s[20:21]
	s_add_i32 s1, s42, s96
	s_mov_b32 m0, s1
	s_nop 0
	global_load_lds_dwordx4 v[66:67], off
	s_waitcnt lgkmcnt(14)
	v_mfma_f32_32x32x16_bf16 v[32:47], v[172:175], v[192:195], v[32:47]
	v_exp_f32_e32 v96, v96
	v_exp_f32_e32 v97, v97
	ds_read_b64_tr_b16 v[66:67], v209 offset:49152
	ds_read_b64_tr_b16 v[68:69], v209 offset:49664
	s_waitcnt lgkmcnt(14)
	v_mfma_f32_32x32x16_bf16 v[48:63], v[172:175], v[196:199], v[48:63]
	v_exp_f32_e32 v98, v98
	v_exp_f32_e32 v99, v99
	ds_read_b64_tr_b16 v[76:77], v209 offset:53248
	ds_read_b64_tr_b16 v[78:79], v209 offset:53760
	v_add_u32_e32 v75, s42, v250
	ds_read_b128 v[204:207], v75
	ds_read_b128 v[200:203], v75 offset:512
	s_waitcnt lgkmcnt(14)
	v_mfma_f32_32x32x16_bf16 v[32:47], v[168:171], v[216:219], v[32:47]
	v_exp_f32_e32 v100, v100
	v_exp_f32_e32 v101, v101
	ds_read_b64_tr_b16 v[116:117], v209 offset:50176
	ds_read_b64_tr_b16 v[118:119], v209 offset:50688
	ds_read_b128 v[196:199], v75 offset:2048
	ds_read_b128 v[192:195], v75 offset:2560
	v_mfma_f32_32x32x16_bf16 v[48:63], v[168:171], v[136:139], v[48:63]
	v_exp_f32_e32 v102, v102
	v_exp_f32_e32 v103, v103
	ds_read_b64_tr_b16 v[120:121], v209 offset:54272
	ds_read_b64_tr_b16 v[122:123], v209 offset:54784
	ds_read_b128 v[188:191], v75 offset:4096
	ds_read_b128 v[184:187], v75 offset:4608
	s_waitcnt lgkmcnt(14)
	v_mfma_f32_32x32x16_bf16 v[32:47], v[164:167], v[132:135], v[32:47]
	v_exp_f32_e32 v104, v104
	v_exp_f32_e32 v105, v105
	ds_read_b64_tr_b16 v[124:125], v209 offset:51200
	ds_read_b64_tr_b16 v[126:127], v209 offset:51712
	ds_read_b128 v[180:183], v75 offset:6144
	ds_read_b128 v[176:179], v75 offset:6656
	v_mfma_f32_32x32x16_bf16 v[48:63], v[164:167], v[128:131], v[48:63]
	v_exp_f32_e32 v106, v106
	v_exp_f32_e32 v107, v107
	ds_read_b64_tr_b16 v[128:129], v209 offset:55296
	ds_read_b64_tr_b16 v[130:131], v209 offset:55808
	v_mfma_f32_32x32x16_bf16 v[32:47], v[160:163], v[112:115], v[32:47]
	v_exp_f32_e32 v108, v108
	v_exp_f32_e32 v109, v109
	ds_read_b64_tr_b16 v[112:113], v209 offset:52224
	ds_read_b64_tr_b16 v[114:115], v209 offset:52736
	v_mfma_f32_32x32x16_bf16 v[48:63], v[160:163], v[70:73], v[48:63]
	v_exp_f32_e32 v110, v110
	v_exp_f32_e32 v111, v111
	ds_read_b64_tr_b16 v[70:71], v209 offset:56320
	ds_read_b64_tr_b16 v[72:73], v209 offset:56832
	s_waitcnt lgkmcnt(14)
	v_mfma_f32_32x32x16_bf16 v[0:15], v[172:175], v[66:69], v[0:15]
	v_exp_f32_e32 v80, v80
	v_exp_f32_e32 v81, v81
	v_mfma_f32_32x32x16_bf16 v[16:31], v[172:175], v[76:79], v[16:31]
	v_exp_f32_e32 v82, v82
	v_exp_f32_e32 v83, v83
	v_mfma_f32_32x32x16_bf16 v[0:15], v[168:171], v[116:119], v[0:15]
	v_exp_f32_e32 v84, v84
	v_exp_f32_e32 v85, v85
	s_waitcnt lgkmcnt(12)
	v_mfma_f32_32x32x16_bf16 v[16:31], v[168:171], v[120:123], v[16:31]
	v_exp_f32_e32 v86, v86
	v_exp_f32_e32 v87, v87
	s_waitcnt lgkmcnt(8)
	v_mfma_f32_32x32x16_bf16 v[0:15], v[164:167], v[124:127], v[0:15]
	v_exp_f32_e32 v88, v88
	v_exp_f32_e32 v89, v89
	s_waitcnt lgkmcnt(4)
	v_mfma_f32_32x32x16_bf16 v[16:31], v[164:167], v[128:131], v[16:31]
	v_exp_f32_e32 v90, v90
	v_exp_f32_e32 v91, v91
	s_waitcnt lgkmcnt(2)
	v_mfma_f32_32x32x16_bf16 v[0:15], v[160:163], v[112:115], v[0:15]
	v_exp_f32_e32 v92, v92
	v_exp_f32_e32 v93, v93
	s_waitcnt lgkmcnt(0)
	v_mfma_f32_32x32x16_bf16 v[16:31], v[160:163], v[70:73], v[16:31]
	v_exp_f32_e32 v94, v94
	v_exp_f32_e32 v95, v95
	s_add_i32 s1, s42, 0x2000
	s_waitcnt vmcnt(3) lgkmcnt(0)
	s_barrier
; #define WAIT_BAR(N) asm volatile("s_waitcnt vmcnt(" #N ") lgkmcnt(0)\n\ts_barrier":::"memory")
;   #define RESC() do{ if(resc){ asm volatile("s_waitcnt lgkmcnt(0)":::"memory"); \
;       _Pragma("unroll") for(int d_=0;d_<2;++d_) _Pragma("unroll") for(int r=0;r<16;++r){const float f_=wsf[crow(r,hi)];o[d_][r]*=f_;o2[d_][r]*=f_;} } }while(0)
;   #define ROT() do{sl_prev=sl_cur;sl_cur=sl_next;sl_next=(sl_next==(NSLOT-1)*SLOTB)?0:sl_next+SLOTB;}while(0)
; template<int THRL> __device__ __forceinline__ void attn_unit(int b,int h,int qb,unsigned char*wsb,char*shm,float kmax,const int CMB,float lam){
;     ...
;   for(;t+5<NT;t+=2){
;     STEP(pB0,pB1,pA0,pA1,t,true,true,true);     WAIT_BAR(3); RESC(); ROT();
;     STEP(pA0,pA1,pB0,pB1,t+1,true,true,true);   WAIT_BAR(3); RESC(); ROT();
;   }
	s_cmpk_lg_i32 s42, 0x4000
	v_add_f32_e32 v64, v64, v65
	s_mov_b32 s5, s36
	s_cselect_b32 s36, s1, 0
	s_add_i32 s33, s33, 2
	v_lshl_add_u64 v[210:211], v[210:211], 0, s[22:23]
	v_lshl_add_u64 v[212:213], v[212:213], 0, s[22:23]
	s_cmp_ge_u32 s33, s89
	v_add_f32_e32 v64, v64, v74
	s_cbranch_scc0 .LBB0_311
	ds_read_b32 v230, v246
	ds_read_b32 v231, v246 offset:2048
	ds_read_b32 v232, v246 offset:4096
	ds_read_b32 v233, v246 offset:6144
	ds_read_b32 v234, v246 offset:8192
	ds_read_b32 v235, v246 offset:10240
	ds_read_b32 v236, v246 offset:12288
	ds_read_b32 v237, v246 offset:14336
	ds_read_b32 v238, v246 offset:16384
	ds_read_b32 v239, v246 offset:18432
	ds_read_b32 v240, v246 offset:20480
	ds_read_b32 v241, v246 offset:22528
	ds_read_b32 v242, v246 offset:24576
	ds_read_b32 v243, v246 offset:26624
	ds_read_b32 v244, v246 offset:28672
	ds_read_b32 v245, v246 offset:30720
	ds_read_b32 v246, v246 offset:32768
	s_waitcnt lgkmcnt(0)
	s_nop 0
	s_nop 0
	s_nop 0
	s_nop 0
	s_nop 0
	s_nop 0
	s_nop 0
	s_nop 0
	s_nop 0
	s_nop 0
	s_nop 0
	s_nop 0
	s_nop 0
	s_nop 0
	s_nop 0
	s_nop 0
	s_nop 0
	s_nop 0
	s_nop 0
	s_nop 0
	s_nop 0
	s_nop 0
	s_nop 0
	s_nop 0
	s_add_i32 s6, s4, -3
	s_branch .LBB0_314
